# NSA online-softmax loops: defer O/l rescale unless a lane's running max rises by more than 8 log2 units (threshold rescale), on top of fast-div + mask fast path + epilogue pipelining
# speedup vs baseline: 1.0328x; 1.0328x over previous
.Lself0_join:
	v_mov_b32_e32 v82, v0
	s_nop 1
	v_permlane32_swap_b32_e32 v0, v82
	v_max_f32_e32 v82, v82, v82
	v_max_f32_e32 v0, v0, v0
	v_max_f32_e32 v0, v0, v82
	v_mul_f32_e32 v0, 0x3e0293ee, v0
	v_max_f32_e32 v82, v235, v235
	v_max_f32_e32 v236, v82, v0
	v_sub_f32_e32 v0, v235, v236
	ds_read_b128 v[86:89], v81 offset:26624
	ds_read_b128 v[82:85], v81 offset:31232
	v_cmp_le_f32_e32 vcc, 0xc1000000, v0
	s_cmp_eq_u64 vcc, exec
	s_cbranch_scc0 .Llazy0_resc
	v_mov_b32_e32 v236, v235
	v_mov_b32_e32 v0, 1.0

.Llazy0_resc:
	v_exp_f32_e32 v0, v0
	s_nop 0
	v_pk_mul_f32 v[78:79], v[78:79], v[0:1] op_sel_hi:[1,0]
	v_pk_mul_f32 v[76:77], v[76:77], v[0:1] op_sel_hi:[1,0]
	v_pk_mul_f32 v[74:75], v[74:75], v[0:1] op_sel_hi:[1,0]
	v_pk_mul_f32 v[72:73], v[72:73], v[0:1] op_sel_hi:[1,0]
	v_pk_mul_f32 v[70:71], v[70:71], v[0:1] op_sel_hi:[1,0]
	v_pk_mul_f32 v[68:69], v[68:69], v[0:1] op_sel_hi:[1,0]
	v_pk_mul_f32 v[66:67], v[66:67], v[0:1] op_sel_hi:[1,0]
	v_pk_mul_f32 v[64:65], v[64:65], v[0:1] op_sel_hi:[1,0]
	v_pk_mul_f32 v[62:63], v[62:63], v[0:1] op_sel_hi:[1,0]
	v_pk_mul_f32 v[60:61], v[60:61], v[0:1] op_sel_hi:[1,0]
	v_pk_mul_f32 v[58:59], v[58:59], v[0:1] op_sel_hi:[1,0]
	v_pk_mul_f32 v[56:57], v[56:57], v[0:1] op_sel_hi:[1,0]
	v_pk_mul_f32 v[54:55], v[54:55], v[0:1] op_sel_hi:[1,0]
	v_pk_mul_f32 v[52:53], v[52:53], v[0:1] op_sel_hi:[1,0]
	v_pk_mul_f32 v[50:51], v[50:51], v[0:1] op_sel_hi:[1,0]
	v_pk_mul_f32 v[48:49], v[48:49], v[0:1] op_sel_hi:[1,0]
	v_pk_mul_f32 v[46:47], v[46:47], v[0:1] op_sel_hi:[1,0]
	v_pk_mul_f32 v[44:45], v[44:45], v[0:1] op_sel_hi:[1,0]
	v_pk_mul_f32 v[42:43], v[42:43], v[0:1] op_sel_hi:[1,0]
	v_pk_mul_f32 v[40:41], v[40:41], v[0:1] op_sel_hi:[1,0]
	v_pk_mul_f32 v[38:39], v[38:39], v[0:1] op_sel_hi:[1,0]
	v_pk_mul_f32 v[36:37], v[36:37], v[0:1] op_sel_hi:[1,0]
	v_pk_mul_f32 v[34:35], v[34:35], v[0:1] op_sel_hi:[1,0]
	v_pk_mul_f32 v[32:33], v[32:33], v[0:1] op_sel_hi:[1,0]
	v_pk_mul_f32 v[30:31], v[30:31], v[0:1] op_sel_hi:[1,0]
	v_pk_mul_f32 v[28:29], v[28:29], v[0:1] op_sel_hi:[1,0]
	v_pk_mul_f32 v[26:27], v[26:27], v[0:1] op_sel_hi:[1,0]
	v_pk_mul_f32 v[24:25], v[24:25], v[0:1] op_sel_hi:[1,0]
	v_pk_mul_f32 v[22:23], v[22:23], v[0:1] op_sel_hi:[1,0]
	v_pk_mul_f32 v[20:21], v[20:21], v[0:1] op_sel_hi:[1,0]
	v_pk_mul_f32 v[18:19], v[18:19], v[0:1] op_sel_hi:[1,0]
	v_pk_mul_f32 v[16:17], v[16:17], v[0:1] op_sel_hi:[1,0]
	s_branch .LBB0_1213

.Lself1_join:
	v_mov_b32_e32 v82, v0
	s_nop 1
	v_permlane32_swap_b32_e32 v0, v82
	v_max_f32_e32 v82, v82, v82
	v_max_f32_e32 v0, v0, v0
	v_max_f32_e32 v0, v0, v82
	v_mul_f32_e32 v0, 0x3e0293ee, v0
	v_max_f32_e32 v82, v236, v236
	v_max_f32_e32 v235, v82, v0
	v_sub_f32_e32 v0, v236, v235
	ds_read_b128 v[86:89], v81 offset:26688
	ds_read_b128 v[82:85], v81 offset:31296
	v_cmp_le_f32_e32 vcc, 0xc1000000, v0
	s_cmp_eq_u64 vcc, exec
	s_cbranch_scc0 .Llazy1_resc
	v_mov_b32_e32 v235, v236
	v_mov_b32_e32 v0, 1.0

.Lwinf0_join:
	v_mov_b32_e32 v80, v0
	s_nop 1
	v_permlane32_swap_b32_e32 v0, v80
	v_max_f32_e32 v80, v80, v80
	v_max_f32_e32 v0, v0, v0
	v_max_f32_e32 v0, v0, v80
	v_mul_f32_e32 v0, 0x3e0293ee, v0
	v_max_f32_e32 v80, v142, v142
	v_max_f32_e32 v246, v80, v0
	v_sub_f32_e32 v0, v142, v246
	ds_read_b128 v[84:87], v167 offset:26624
	ds_read_b128 v[80:83], v167 offset:31232
	v_cmp_le_f32_e32 vcc, 0xc1000000, v0
	s_cmp_eq_u64 vcc, exec
	s_cbranch_scc0 .Llazy2_resc
	v_mov_b32_e32 v246, v142
	v_mov_b32_e32 v0, 1.0

.Lwinf1_join:
	v_mov_b32_e32 v80, v14
	s_nop 1
	v_permlane32_swap_b32_e32 v14, v80
	v_max_f32_e32 v80, v80, v80
	v_max_f32_e32 v14, v14, v14
	v_max_f32_e32 v14, v14, v80
	v_mul_f32_e32 v14, 0x3e0293ee, v14
	v_max_f32_e32 v80, v246, v246
	v_max_f32_e32 v142, v80, v14
	v_sub_f32_e32 v14, v246, v142
	ds_read_b128 v[84:87], v167 offset:26688
	ds_read_b128 v[80:83], v167 offset:31296
	v_cmp_le_f32_e32 vcc, 0xc1000000, v14
	s_cmp_eq_u64 vcc, exec
	s_cbranch_scc0 .Llazy3_resc
	v_mov_b32_e32 v142, v246
	v_mov_b32_e32 v14, 1.0

.Llazy3_resc:
	v_exp_f32_e32 v14, v14
	s_nop 0
	v_pk_mul_f32 v[78:79], v[78:79], v[14:15] op_sel_hi:[1,0]
	v_pk_mul_f32 v[76:77], v[76:77], v[14:15] op_sel_hi:[1,0]
	v_pk_mul_f32 v[74:75], v[74:75], v[14:15] op_sel_hi:[1,0]
	v_pk_mul_f32 v[72:73], v[72:73], v[14:15] op_sel_hi:[1,0]
	v_pk_mul_f32 v[70:71], v[70:71], v[14:15] op_sel_hi:[1,0]
	v_pk_mul_f32 v[68:69], v[68:69], v[14:15] op_sel_hi:[1,0]
	v_pk_mul_f32 v[66:67], v[66:67], v[14:15] op_sel_hi:[1,0]
	v_pk_mul_f32 v[64:65], v[64:65], v[14:15] op_sel_hi:[1,0]
	v_pk_mul_f32 v[62:63], v[62:63], v[14:15] op_sel_hi:[1,0]
	v_pk_mul_f32 v[60:61], v[60:61], v[14:15] op_sel_hi:[1,0]
	v_pk_mul_f32 v[58:59], v[58:59], v[14:15] op_sel_hi:[1,0]
	v_pk_mul_f32 v[56:57], v[56:57], v[14:15] op_sel_hi:[1,0]
	v_pk_mul_f32 v[54:55], v[54:55], v[14:15] op_sel_hi:[1,0]
	v_pk_mul_f32 v[52:53], v[52:53], v[14:15] op_sel_hi:[1,0]
	v_pk_mul_f32 v[50:51], v[50:51], v[14:15] op_sel_hi:[1,0]
	v_pk_mul_f32 v[48:49], v[48:49], v[14:15] op_sel_hi:[1,0]
	v_pk_mul_f32 v[46:47], v[46:47], v[14:15] op_sel_hi:[1,0]
	v_pk_mul_f32 v[44:45], v[44:45], v[14:15] op_sel_hi:[1,0]
	v_pk_mul_f32 v[42:43], v[42:43], v[14:15] op_sel_hi:[1,0]
	v_pk_mul_f32 v[40:41], v[40:41], v[14:15] op_sel_hi:[1,0]
	v_pk_mul_f32 v[38:39], v[38:39], v[14:15] op_sel_hi:[1,0]
	v_pk_mul_f32 v[36:37], v[36:37], v[14:15] op_sel_hi:[1,0]
	v_pk_mul_f32 v[34:35], v[34:35], v[14:15] op_sel_hi:[1,0]
	v_pk_mul_f32 v[32:33], v[32:33], v[14:15] op_sel_hi:[1,0]
	v_pk_mul_f32 v[30:31], v[30:31], v[14:15] op_sel_hi:[1,0]
	v_pk_mul_f32 v[28:29], v[28:29], v[14:15] op_sel_hi:[1,0]
	v_pk_mul_f32 v[26:27], v[26:27], v[14:15] op_sel_hi:[1,0]
	v_pk_mul_f32 v[24:25], v[24:25], v[14:15] op_sel_hi:[1,0]
	v_pk_mul_f32 v[22:23], v[22:23], v[14:15] op_sel_hi:[1,0]
	v_pk_mul_f32 v[20:21], v[20:21], v[14:15] op_sel_hi:[1,0]
	v_pk_mul_f32 v[18:19], v[18:19], v[14:15] op_sel_hi:[1,0]
	v_pk_mul_f32 v[16:17], v[16:17], v[14:15] op_sel_hi:[1,0]
	s_branch .LBB0_1244
